# DF late half: step stop-flag written at the start of the exp phase (LDS write no longer waited at the step barrier)
# baseline (speedup 1.0000x reference)
.LBB0_416:
	v_add_u32_e32 v80, 1, v236
	v_cvt_f32_i32_e32 v80, v80
	s_mov_b64 s[12:13], exec
	v_fma_f32 v80, v234, v80, s20
	v_sub_f32_e32 v80, v80, v237
	v_cmp_gt_f32_e32 vcc, s52, v80
	s_and_saveexec_b64 s[14:15], s[86:87]
	s_cbranch_execz .Ldfl_fl1
	s_add_i32 s28, s26, -8
	s_and_b32 s28, s28, 8
	s_add_i32 s28, s68, s28
	s_cmp_eq_u64 vcc, s[12:13]
	s_cselect_b64 s[12:13], -1, 0
	v_cndmask_b32_e64 v80, 0, 1, s[12:13]
	v_mov_b32_e32 v81, s28
	ds_write_b8 v81, v80
.Ldfl_fl1:
	s_or_b64 exec, exec, s[14:15]
	v_fma_f32 v95, v238, s83, -v237
	v_fmamk_f32 v0, v2, 0x3e38aa3b, v95
	v_exp_f32_e32 v98, v0
	v_fmamk_f32 v0, v6, 0x3e38aa3b, v95
	v_exp_f32_e32 v99, v0
	v_fmamk_f32 v0, v3, 0x3e38aa3b, v95
	v_exp_f32_e32 v2, v0
	v_fmamk_f32 v0, v7, 0x3e38aa3b, v95
	v_exp_f32_e32 v0, v0
	v_add_f32_e32 v3, v98, v99
	s_mov_b64 s[10:11], -1
	v_add_f32 v6, v2, v0
	v_add_f32 v7, v3, v1
	v_fmamk_f32 v3, v4, 0x3e38aa3b, v95
	v_fmamk_f32 v4, v8, 0x3e38aa3b, v95
	v_add_f32 v80, v6, v6
	v_add_f32 v81, v6, v7
	v_exp_f32_e32 v3, v3
	v_exp_f32_e32 v100, v4
	v_fmamk_f32 v4, v5, 0x3e38aa3b, v95
	v_fmamk_f32 v5, v9, 0x3e38aa3b, v95
	v_exp_f32_e32 v4, v4
	v_exp_f32_e32 v80, v5
	v_add_f32_e32 v5, v3, v100
	v_add_f32 v6, v4, v80
	v_add_f32 v7, v5, v81
	s_nop 0
	v_add_f32 v8, v6, v6
	v_add_f32 v9, v6, v7
	v_fmamk_f32 v5, v10, 0x3e38aa3b, v95
	v_fmamk_f32 v6, v12, 0x3e38aa3b, v95
	v_exp_f32_e32 v5, v5
	v_exp_f32_e32 v81, v6
	v_fmamk_f32 v6, v11, 0x3e38aa3b, v95
	v_fmamk_f32 v7, v13, 0x3e38aa3b, v95
	v_exp_f32_e32 v6, v6
	v_exp_f32_e32 v8, v7
	v_add_f32_e32 v7, v5, v81
	v_add_f32 v10, v6, v8
	v_add_f32 v11, v7, v9
	v_fmamk_f32 v7, v14, 0x3e38aa3b, v95
	v_fmamk_f32 v9, v144, 0x3e38aa3b, v95
	v_add_f32 v82, v10, v10
	v_add_f32 v83, v10, v11
	v_exp_f32_e32 v7, v7
	v_exp_f32_e32 v9, v9
	v_fmamk_f32 v10, v15, 0x3e38aa3b, v95
	v_fmamk_f32 v11, v145, 0x3e38aa3b, v95
	v_exp_f32_e32 v10, v10
	v_exp_f32_e32 v82, v11
	v_add_f32_e32 v11, v7, v9
	v_cvt_pk_bf16_f32 v144, v98, v2
	v_cvt_pk_bf16_f32 v145, v3, v4
	v_add_f32 v12, v10, v82
	v_add_f32 v13, v11, v83
	v_fmamk_f32 v11, v146, 0x3e38aa3b, v95
	v_add_f32 v14, v12, v12
	v_add_f32 v15, v12, v13
	v_fmamk_f32 v12, v202, 0x3e38aa3b, v95
	v_exp_f32_e32 v11, v11
	v_exp_f32_e32 v83, v12
	v_fmamk_f32 v12, v147, 0x3e38aa3b, v95
	v_fmamk_f32 v13, v203, 0x3e38aa3b, v95
	v_exp_f32_e32 v12, v12
	v_exp_f32_e32 v14, v13
	v_add_f32_e32 v13, v11, v83
	v_cvt_pk_bf16_f32 v146, v5, v6
	v_cvt_pk_bf16_f32 v147, v7, v10
	v_add_f32 v84, v12, v14
	v_add_f32 v85, v13, v15
	v_fmamk_f32 v13, v204, 0x3e38aa3b, v95
	v_add_f32 v85, v84, v85
	v_add_f32 v84, v84, v84
	v_fmamk_f32 v15, v206, 0x3e38aa3b, v95
	v_fmamk_f32 v84, v205, 0x3e38aa3b, v95
	v_exp_f32_e32 v13, v13
	v_exp_f32_e32 v15, v15
	v_exp_f32_e32 v86, v84
	v_fmamk_f32 v84, v207, 0x3e38aa3b, v95
	v_exp_f32_e32 v84, v84
	v_add_f32_e32 v87, v13, v15
	v_cvt_pk_bf16_f32 v10, v11, v12
	v_cvt_pk_bf16_f32 v11, v13, v86
	v_add_f32 v88, v86, v84
	v_add_f32 v89, v87, v85
	v_fmamk_f32 v85, v208, 0x3e38aa3b, v95
	v_add_f32 v89, v88, v89
	v_add_f32 v88, v88, v88
	v_fmamk_f32 v87, v210, 0x3e38aa3b, v95
	v_fmamk_f32 v88, v209, 0x3e38aa3b, v95
	v_exp_f32_e32 v85, v85
	v_exp_f32_e32 v87, v87
	v_exp_f32_e32 v90, v88
	v_fmamk_f32 v88, v211, 0x3e38aa3b, v95
	v_exp_f32_e32 v88, v88
	v_add_f32_e32 v91, v85, v87
	v_cvt_pk_bf16_f32 v12, v85, v90
	v_cvt_pk_bf16_f32 v6, v99, v0
	v_add_f32 v92, v90, v88
	v_add_f32 v93, v91, v89
	v_fmamk_f32 v89, v212, 0x3e38aa3b, v95
	v_add_f32 v93, v92, v93
	v_add_f32 v92, v92, v92
	v_fmamk_f32 v91, v214, 0x3e38aa3b, v95
	v_exp_f32_e32 v89, v89
	v_exp_f32_e32 v91, v91
	v_fmamk_f32 v92, v213, 0x3e38aa3b, v95
	v_fmac_f32_e32 v95, 0x3e38aa3b, v215
	v_exp_f32_e32 v94, v92
	v_exp_f32_e32 v92, v95
	v_add_f32_e32 v95, v89, v91
	v_cvt_pk_bf16_f32 v7, v100, v80
	v_cvt_pk_bf16_f32 v13, v89, v94
	v_add_f32 v96, v94, v92
	v_add_f32 v97, v95, v93
	v_cvt_pk_bf16_f32 v8, v81, v8
	v_add_f32_e32 v93, v96, v97
	v_add_f32_e32 v217, v217, v93
	v_cvt_pk_bf16_f32 v9, v9, v82
	v_cvt_pk_bf16_f32 v2, v83, v14
	v_cvt_pk_bf16_f32 v3, v15, v84
	v_cvt_pk_bf16_f32 v4, v87, v88
	v_cvt_pk_bf16_f32 v5, v91, v92
	s_branch .Ldfl_fl2

.Ldfl_fl2:
	s_add_i32 s12, s24, 1
	s_cmp_lg_u32 s24, 4
	s_cselect_b32 s24, s12, 0
